# v26 + scan phase software-pipelined: the 8-way LDS reduction and stores of chunk i-1 ride in the MFMA shadows of chunk i (reduction inputs in v[200:215])
# baseline (speedup 1.0000x reference)
; #define LAS __attribute__((address_space(3)))
; #define LDS_WAIT() asm volatile("s_waitcnt lgkmcnt(0)" ::: "memory")
; #define SCAN_LOADV(VSET, CH) do { const size_t c_ = (size_t)(CH); \
;             _Pragma("unroll") for (int s = 0; s < 4; ++s) kf[VSET][s] = *(const bf16x8*)(kp + c_ * 32768 + 1024 * s + voff); } while (0)
; #define SCAN_LOAD(SET, CH) do { const size_t c_ = (size_t)(CH); \
;             _Pragma("unroll") for (int nt = 0; nt < 2; ++nt) _Pragma("unroll") for (int s = 0; s < 2; ++s) qf[SET][nt][s] = *(const bf16x8*)(qp + c_ * 32768 + nt * 2048 + 1024 * s + voff); \
;             pf[SET] = *(const bf16x8*)(pp + c_ * 8192 + voff); } while (0)
; __device__ __forceinline__ void scan_phase(const bf16* q, const bf16* kdT, const bf16* vT, const bf16* Pp, bf16* o, LAS unsigned char* lds, int bid, int G, int wave, int lane, int tid) {
;     ...
;         SCAN_LOAD(0, 0); SCAN_LOAD(1, 1); SCAN_LOADV(0, 0);
;         vst = *(const bf16x8*)(vp + 1024 * (wave & 3) + voff);
;         if (wave < 4) { *(LAS bf16x8*)(lds + 65536 + wave * 1024 + voff) = vst; vst = *(const bf16x8*)(vp + (size_t)32768 + 1024 * wave + voff); }
;         LDS_WAIT(); __builtin_amdgcn_s_barrier(); asm volatile("" ::: "memory");
; #pragma unroll
;         for (int s = 0; s < 4; ++s) vf[s] = *(const LAS bf16x8*)(lds + 65536 + s * 1024 + voff);
;         for (int i = 0; i < 60; i += 6) { SCAN_STEP(0, 2, 0, 1, i); SCAN_STEP(1, 0, 1, 0, i + 1); SCAN_STEP(2, 1, 0, 1, i + 2); SCAN_STEP(0, 2, 1, 0, i + 3); SCAN_STEP(1, 0, 0, 1, i + 4); SCAN_STEP(2, 1, 1, 0, i + 5); }
.Lp2b_pv_2:
	s_add_u32 s16, s16, 0x8000
	s_addc_u32 s17, s17, 0
	s_waitcnt lgkmcnt(0)
	s_barrier
	ds_read_b128 v[150:153], v195
	ds_read_b128 v[154:157], v195 offset:1024
	ds_read_b128 v[158:161], v195 offset:2048
	ds_read_b128 v[162:165], v195 offset:3072
	ds_read_b128 v[166:169], v196
	s_waitcnt vmcnt(0)
	s_waitcnt vmcnt(9)
	s_andn2_b64 vcc, exec, s[34:35]
	s_cbranch_vccnz .Lp2b_sv_3
	ds_write_b128 v194, v[170:173] offset:4096
	global_load_dwordx4 v[170:173], v1, s[16:17]
.Lp2b_sv_3:
	global_load_dwordx4 v[134:137], v1, s[14:15]
	global_load_dwordx4 v[138:141], v1, s[14:15] offset:1024
	global_load_dwordx4 v[142:145], v1, s[14:15] offset:2048
	global_load_dwordx4 v[146:149], v1, s[14:15] offset:3072
	v_cvt_pk_bf16_f32 v50, v2, v3
	v_cvt_pk_bf16_f32 v51, v4, v5
	v_cvt_pk_bf16_f32 v52, v6, v7
	v_cvt_pk_bf16_f32 v53, v8, v9
	v_cvt_pk_bf16_f32 v54, v10, v11
	v_cvt_pk_bf16_f32 v55, v12, v13
	v_cvt_pk_bf16_f32 v56, v14, v15
	v_cvt_pk_bf16_f32 v57, v16, v17
	global_load_dwordx4 v[98:101], v1, s[8:9]
	global_load_dwordx4 v[102:105], v1, s[8:9] offset:1024
	global_load_dwordx4 v[106:109], v1, s[8:9] offset:2048
	global_load_dwordx4 v[110:113], v1, s[8:9] offset:3072
	global_load_dwordx4 v[114:117], v1, s[18:19]
	s_waitcnt lgkmcnt(0)
	v_mfma_f32_32x32x16_bf16 v[18:33], v[58:61], v[50:53], 0
	v_mfma_f32_32x32x16_bf16 v[34:49], v[66:69], v[50:53], 0
	s_add_u32 s16, s16, 0x8000
	s_addc_u32 s17, s17, 0
	s_add_u32 s14, s14, 0x8000
	s_addc_u32 s15, s15, 0
	s_add_u32 s8, s8, 0x8000
	s_addc_u32 s9, s9, 0
	s_add_u32 s18, s18, 0x2000
	s_addc_u32 s19, s19, 0
	v_mfma_f32_32x32x16_bf16 v[18:33], v[62:65], v[54:57], v[18:33]
	v_mfma_f32_32x32x16_bf16 v[34:49], v[70:73], v[54:57], v[34:49]
	v_mul_f32_e32 v2, v190, v2
	v_mul_f32_e32 v3, v190, v3
	v_mul_f32_e32 v4, v190, v4
	v_mul_f32_e32 v5, v190, v5
	v_mul_f32_e32 v6, v190, v6
	v_mul_f32_e32 v7, v190, v7
	v_mul_f32_e32 v8, v190, v8
	v_mul_f32_e32 v9, v190, v9
	v_mul_f32_e32 v10, v190, v10
	v_mul_f32_e32 v11, v190, v11
	v_mul_f32_e32 v12, v190, v12
	v_mul_f32_e32 v13, v190, v13
	v_mul_f32_e32 v14, v190, v14
	v_mul_f32_e32 v15, v190, v15
	v_mul_f32_e32 v16, v190, v16
	v_mul_f32_e32 v17, v190, v17
	s_cmp_eq_u32 s7, 0
	s_cbranch_scc0 .Lp2b_in_4
	v_mfma_f32_32x32x16_bf16 v[18:33], v[74:77], v[166:169], v[18:33]
	s_branch .Lp2b_in_5

.Lp2b_in_5:
	v_mfma_f32_32x32x16_bf16 v[2:17], v[118:121], v[150:153], v[2:17]
	v_mfma_f32_32x32x16_bf16 v[2:17], v[122:125], v[154:157], v[2:17]
	s_nop 9
	v_cvt_pk_bf16_f32 v18, v18, v19
	v_cvt_pk_bf16_f32 v19, v20, v21
	v_cvt_pk_bf16_f32 v20, v22, v23
	v_cvt_pk_bf16_f32 v21, v24, v25
	v_cvt_pk_bf16_f32 v22, v26, v27
	v_cvt_pk_bf16_f32 v23, v28, v29
	v_cvt_pk_bf16_f32 v24, v30, v31
	v_cvt_pk_bf16_f32 v25, v32, v33
	ds_write_b128 v192, v[18:21]
	ds_write_b128 v192, v[22:25] offset:1024
	v_mfma_f32_32x32x16_bf16 v[2:17], v[126:129], v[158:161], v[2:17]
	v_cvt_pk_bf16_f32 v34, v34, v35
	v_cvt_pk_bf16_f32 v35, v36, v37
	v_cvt_pk_bf16_f32 v36, v38, v39
	v_cvt_pk_bf16_f32 v37, v40, v41
	v_cvt_pk_bf16_f32 v38, v42, v43
	v_cvt_pk_bf16_f32 v39, v44, v45
	v_cvt_pk_bf16_f32 v40, v46, v47
	v_cvt_pk_bf16_f32 v41, v48, v49
	ds_write_b128 v192, v[34:37] offset:2048
	ds_write_b128 v192, v[38:41] offset:3072
	v_mfma_f32_32x32x16_bf16 v[2:17], v[130:133], v[162:165], v[2:17]
	s_waitcnt lgkmcnt(0)
	s_barrier
	ds_read2st64_b64 v[200:203], v193 offset0:0 offset1:8
	ds_read2st64_b64 v[204:207], v193 offset0:16 offset1:24
	ds_read2st64_b64 v[208:211], v193 offset0:32 offset1:40
	ds_read2st64_b64 v[212:215], v193 offset0:48 offset1:56
	ds_read_b128 v[150:153], v195 offset:4096
	ds_read_b128 v[154:157], v195 offset:5120
	ds_read_b128 v[158:161], v195 offset:6144
	ds_read_b128 v[162:165], v195 offset:7168
	ds_read_b128 v[166:169], v196 offset:4096
	s_waitcnt vmcnt(5)
	s_mov_b32 s22, 0
.Lp2b_loop:
	s_waitcnt vmcnt(9)
	s_andn2_b64 vcc, exec, s[34:35]
	s_cbranch_vccnz .Lp2b_sv_6
	ds_write_b128 v194, v[170:173]
	global_load_dwordx4 v[170:173], v1, s[16:17]
.Lp2b_sv_6:
	global_load_dwordx4 v[118:121], v1, s[14:15]
	global_load_dwordx4 v[122:125], v1, s[14:15] offset:1024
	global_load_dwordx4 v[126:129], v1, s[14:15] offset:2048
	global_load_dwordx4 v[130:133], v1, s[14:15] offset:3072
	v_cvt_pk_bf16_f32 v50, v2, v3
	v_cvt_pk_bf16_f32 v51, v4, v5
	v_cvt_pk_bf16_f32 v52, v6, v7
	v_cvt_pk_bf16_f32 v53, v8, v9
	v_cvt_pk_bf16_f32 v54, v10, v11
	v_cvt_pk_bf16_f32 v55, v12, v13
	v_cvt_pk_bf16_f32 v56, v14, v15
	v_cvt_pk_bf16_f32 v57, v16, v17
	global_load_dwordx4 v[58:61], v1, s[8:9]
	global_load_dwordx4 v[62:65], v1, s[8:9] offset:1024
	global_load_dwordx4 v[66:69], v1, s[8:9] offset:2048
	global_load_dwordx4 v[70:73], v1, s[8:9] offset:3072
	global_load_dwordx4 v[74:77], v1, s[18:19]
	s_waitcnt lgkmcnt(0)
	v_mfma_f32_32x32x16_bf16 v[18:33], v[78:81], v[50:53], 0
	v_mfma_f32_32x32x16_bf16 v[34:49], v[86:89], v[50:53], 0
	v_lshlrev_b32_e32 v178, 16, v200
	v_and_b32_e32 v179, 0xffff0000, v200
	v_lshlrev_b32_e32 v180, 16, v201
	v_and_b32_e32 v181, 0xffff0000, v201
	v_add_f32_e32 v174, 0, v178
	v_add_f32_e32 v175, 0, v179
	v_add_f32_e32 v176, 0, v180
	v_add_f32_e32 v177, 0, v181
	v_lshlrev_b32_e32 v178, 16, v202
	v_and_b32_e32 v179, 0xffff0000, v202
	v_lshlrev_b32_e32 v180, 16, v203
	v_and_b32_e32 v181, 0xffff0000, v203
	v_add_f32_e32 v174, v174, v178
	v_add_f32_e32 v175, v175, v179
	v_add_f32_e32 v176, v176, v180
	v_add_f32_e32 v177, v177, v181
	s_add_u32 s16, s16, 0x8000
	s_addc_u32 s17, s17, 0
	s_add_u32 s14, s14, 0x8000
	s_addc_u32 s15, s15, 0
	s_add_u32 s8, s8, 0x8000
	s_addc_u32 s9, s9, 0
	s_add_u32 s18, s18, 0x2000
	s_addc_u32 s19, s19, 0
	v_mfma_f32_32x32x16_bf16 v[18:33], v[82:85], v[54:57], v[18:33]
	v_mfma_f32_32x32x16_bf16 v[34:49], v[90:93], v[54:57], v[34:49]
	v_lshlrev_b32_e32 v178, 16, v204
	v_and_b32_e32 v179, 0xffff0000, v204
	v_lshlrev_b32_e32 v180, 16, v205
	v_and_b32_e32 v181, 0xffff0000, v205
	v_add_f32_e32 v174, v174, v178
	v_add_f32_e32 v175, v175, v179
	v_add_f32_e32 v176, v176, v180
	v_add_f32_e32 v177, v177, v181
	v_lshlrev_b32_e32 v178, 16, v206
	v_and_b32_e32 v179, 0xffff0000, v206
	v_lshlrev_b32_e32 v180, 16, v207
	v_and_b32_e32 v181, 0xffff0000, v207
	v_add_f32_e32 v174, v174, v178
	v_add_f32_e32 v175, v175, v179
	v_add_f32_e32 v176, v176, v180
	v_add_f32_e32 v177, v177, v181
	v_mul_f32_e32 v2, v190, v2
	v_mul_f32_e32 v3, v190, v3
	v_mul_f32_e32 v4, v190, v4
	v_mul_f32_e32 v5, v190, v5
	v_mul_f32_e32 v6, v190, v6
	v_mul_f32_e32 v7, v190, v7
	v_mul_f32_e32 v8, v190, v8
	v_mul_f32_e32 v9, v190, v9
	v_mul_f32_e32 v10, v190, v10
	v_mul_f32_e32 v11, v190, v11
	v_mul_f32_e32 v12, v190, v12
	v_mul_f32_e32 v13, v190, v13
	v_mul_f32_e32 v14, v190, v14
	v_mul_f32_e32 v15, v190, v15
	v_mul_f32_e32 v16, v190, v16
	v_mul_f32_e32 v17, v190, v17
	s_cmp_eq_u32 s7, 0
	s_cbranch_scc0 .Lp2b_in_7
	v_mfma_f32_32x32x16_bf16 v[18:33], v[94:97], v[166:169], v[18:33]
	s_branch .Lp2b_in_8

.Lp2b_in_8:
	v_lshlrev_b32_e32 v178, 16, v208
	v_and_b32_e32 v179, 0xffff0000, v208
	v_lshlrev_b32_e32 v180, 16, v209
	v_and_b32_e32 v181, 0xffff0000, v209
	v_add_f32_e32 v174, v174, v178
	v_add_f32_e32 v175, v175, v179
	v_add_f32_e32 v176, v176, v180
	v_add_f32_e32 v177, v177, v181
	v_lshlrev_b32_e32 v178, 16, v210
	v_and_b32_e32 v179, 0xffff0000, v210
	v_lshlrev_b32_e32 v180, 16, v211
	v_and_b32_e32 v181, 0xffff0000, v211
	v_add_f32_e32 v174, v174, v178
	v_add_f32_e32 v175, v175, v179
	v_add_f32_e32 v176, v176, v180
	v_add_f32_e32 v177, v177, v181
	v_mfma_f32_32x32x16_bf16 v[2:17], v[134:137], v[150:153], v[2:17]
	v_lshlrev_b32_e32 v178, 16, v212
	v_and_b32_e32 v179, 0xffff0000, v212
	v_lshlrev_b32_e32 v180, 16, v213
	v_and_b32_e32 v181, 0xffff0000, v213
	v_add_f32_e32 v174, v174, v178
	v_add_f32_e32 v175, v175, v179
	v_add_f32_e32 v176, v176, v180
	v_add_f32_e32 v177, v177, v181
	v_lshlrev_b32_e32 v178, 16, v214
	v_and_b32_e32 v179, 0xffff0000, v214
	v_lshlrev_b32_e32 v180, 16, v215
	v_and_b32_e32 v181, 0xffff0000, v215
	v_add_f32_e32 v174, v174, v178
	v_add_f32_e32 v175, v175, v179
	v_add_f32_e32 v176, v176, v180
	v_add_f32_e32 v177, v177, v181
	v_mfma_f32_32x32x16_bf16 v[2:17], v[138:141], v[154:157], v[2:17]
	v_mul_f32_e32 v174, v186, v174
	v_mul_f32_e32 v175, v187, v175
	v_mul_f32_e32 v176, v188, v176
	v_mul_f32_e32 v177, v189, v177
	v_bfe_u32 v178, v174, 16, 1
	v_bfe_u32 v179, v175, 16, 1
	v_bfe_u32 v180, v176, 16, 1
	v_bfe_u32 v181, v177, 16, 1
	v_add3_u32 v174, v174, v178, s23
	v_add3_u32 v175, v175, v179, s23
	v_add3_u32 v176, v176, v180, s23
	v_add3_u32 v177, v177, v181, s23
	global_store_short_d16_hi v197, v174, s[20:21] offset:-4096
	global_store_short_d16_hi v197, v175, s[20:21]
	global_store_short_d16_hi v198, v176, s[20:21] offset:-4096
	global_store_short_d16_hi v198, v177, s[20:21]
	s_add_u32 s20, s20, 0x40000
	s_addc_u32 s21, s21, 0
	v_cvt_pk_bf16_f32 v18, v18, v19
	v_cvt_pk_bf16_f32 v19, v20, v21
	v_cvt_pk_bf16_f32 v20, v22, v23
	v_cvt_pk_bf16_f32 v21, v24, v25
	v_cvt_pk_bf16_f32 v22, v26, v27
	v_cvt_pk_bf16_f32 v23, v28, v29
	v_cvt_pk_bf16_f32 v24, v30, v31
	v_cvt_pk_bf16_f32 v25, v32, v33
	ds_write_b128 v192, v[18:21] offset:32768
	ds_write_b128 v192, v[22:25] offset:33792
	v_mfma_f32_32x32x16_bf16 v[2:17], v[142:145], v[158:161], v[2:17]
	v_cvt_pk_bf16_f32 v34, v34, v35
	v_cvt_pk_bf16_f32 v35, v36, v37
	v_cvt_pk_bf16_f32 v36, v38, v39
	v_cvt_pk_bf16_f32 v37, v40, v41
	v_cvt_pk_bf16_f32 v38, v42, v43
	v_cvt_pk_bf16_f32 v39, v44, v45
	v_cvt_pk_bf16_f32 v40, v46, v47
	v_cvt_pk_bf16_f32 v41, v48, v49
	ds_write_b128 v192, v[34:37] offset:34816
	ds_write_b128 v192, v[38:41] offset:35840
	v_mfma_f32_32x32x16_bf16 v[2:17], v[146:149], v[162:165], v[2:17]
	s_waitcnt lgkmcnt(0)
	s_barrier
	ds_read2st64_b64 v[200:203], v193 offset0:64 offset1:72
	ds_read2st64_b64 v[204:207], v193 offset0:80 offset1:88
	ds_read2st64_b64 v[208:211], v193 offset0:96 offset1:104
	ds_read2st64_b64 v[212:215], v193 offset0:112 offset1:120
	ds_read_b128 v[150:153], v195
	ds_read_b128 v[154:157], v195 offset:1024
	ds_read_b128 v[158:161], v195 offset:2048
	ds_read_b128 v[162:165], v195 offset:3072
	ds_read_b128 v[166:169], v196
	s_waitcnt vmcnt(9)
	s_andn2_b64 vcc, exec, s[34:35]
	s_cbranch_vccnz .Lp2b_sv_9
	ds_write_b128 v194, v[170:173] offset:4096
	global_load_dwordx4 v[170:173], v1, s[16:17]
.Lp2b_sv_9:
	global_load_dwordx4 v[134:137], v1, s[14:15]
	global_load_dwordx4 v[138:141], v1, s[14:15] offset:1024
	global_load_dwordx4 v[142:145], v1, s[14:15] offset:2048
	global_load_dwordx4 v[146:149], v1, s[14:15] offset:3072
	v_cvt_pk_bf16_f32 v50, v2, v3
	v_cvt_pk_bf16_f32 v51, v4, v5
	v_cvt_pk_bf16_f32 v52, v6, v7
	v_cvt_pk_bf16_f32 v53, v8, v9
	v_cvt_pk_bf16_f32 v54, v10, v11
	v_cvt_pk_bf16_f32 v55, v12, v13
	v_cvt_pk_bf16_f32 v56, v14, v15
	v_cvt_pk_bf16_f32 v57, v16, v17
	global_load_dwordx4 v[78:81], v1, s[8:9]
	global_load_dwordx4 v[82:85], v1, s[8:9] offset:1024
	global_load_dwordx4 v[86:89], v1, s[8:9] offset:2048
	global_load_dwordx4 v[90:93], v1, s[8:9] offset:3072
	global_load_dwordx4 v[94:97], v1, s[18:19]
	s_waitcnt lgkmcnt(0)
	v_mfma_f32_32x32x16_bf16 v[18:33], v[98:101], v[50:53], 0
	v_mfma_f32_32x32x16_bf16 v[34:49], v[106:109], v[50:53], 0
	v_lshlrev_b32_e32 v178, 16, v200
	v_and_b32_e32 v179, 0xffff0000, v200
	v_lshlrev_b32_e32 v180, 16, v201
	v_and_b32_e32 v181, 0xffff0000, v201
	v_add_f32_e32 v174, 0, v178
	v_add_f32_e32 v175, 0, v179
	v_add_f32_e32 v176, 0, v180
	v_add_f32_e32 v177, 0, v181
	v_lshlrev_b32_e32 v178, 16, v202
	v_and_b32_e32 v179, 0xffff0000, v202
	v_lshlrev_b32_e32 v180, 16, v203
	v_and_b32_e32 v181, 0xffff0000, v203
	v_add_f32_e32 v174, v174, v178
	v_add_f32_e32 v175, v175, v179
	v_add_f32_e32 v176, v176, v180
	v_add_f32_e32 v177, v177, v181
	s_add_u32 s16, s16, 0x8000
	s_addc_u32 s17, s17, 0
	s_add_u32 s14, s14, 0x8000
	s_addc_u32 s15, s15, 0
	s_add_u32 s8, s8, 0x8000
	s_addc_u32 s9, s9, 0
	s_add_u32 s18, s18, 0x2000
	s_addc_u32 s19, s19, 0
	v_mfma_f32_32x32x16_bf16 v[18:33], v[102:105], v[54:57], v[18:33]
	v_mfma_f32_32x32x16_bf16 v[34:49], v[110:113], v[54:57], v[34:49]
	v_lshlrev_b32_e32 v178, 16, v204
	v_and_b32_e32 v179, 0xffff0000, v204
	v_lshlrev_b32_e32 v180, 16, v205
	v_and_b32_e32 v181, 0xffff0000, v205
	v_add_f32_e32 v174, v174, v178
	v_add_f32_e32 v175, v175, v179
	v_add_f32_e32 v176, v176, v180
	v_add_f32_e32 v177, v177, v181
	v_lshlrev_b32_e32 v178, 16, v206
	v_and_b32_e32 v179, 0xffff0000, v206
	v_lshlrev_b32_e32 v180, 16, v207
	v_and_b32_e32 v181, 0xffff0000, v207
	v_add_f32_e32 v174, v174, v178
	v_add_f32_e32 v175, v175, v179
	v_add_f32_e32 v176, v176, v180
	v_add_f32_e32 v177, v177, v181
	v_mul_f32_e32 v2, v190, v2
	v_mul_f32_e32 v3, v190, v3
	v_mul_f32_e32 v4, v190, v4
	v_mul_f32_e32 v5, v190, v5
	v_mul_f32_e32 v6, v190, v6
	v_mul_f32_e32 v7, v190, v7
	v_mul_f32_e32 v8, v190, v8
	v_mul_f32_e32 v9, v190, v9
	v_mul_f32_e32 v10, v190, v10
	v_mul_f32_e32 v11, v190, v11
	v_mul_f32_e32 v12, v190, v12
	v_mul_f32_e32 v13, v190, v13
	v_mul_f32_e32 v14, v190, v14
	v_mul_f32_e32 v15, v190, v15
	v_mul_f32_e32 v16, v190, v16
	v_mul_f32_e32 v17, v190, v17
	s_cmp_eq_u32 s7, 0
	s_cbranch_scc0 .Lp2b_in_10
	v_mfma_f32_32x32x16_bf16 v[18:33], v[114:117], v[166:169], v[18:33]
	s_branch .Lp2b_in_11

.Lp2b_in_11:
	v_lshlrev_b32_e32 v178, 16, v208
	v_and_b32_e32 v179, 0xffff0000, v208
	v_lshlrev_b32_e32 v180, 16, v209
	v_and_b32_e32 v181, 0xffff0000, v209
	v_add_f32_e32 v174, v174, v178
	v_add_f32_e32 v175, v175, v179
	v_add_f32_e32 v176, v176, v180
	v_add_f32_e32 v177, v177, v181
	v_lshlrev_b32_e32 v178, 16, v210
	v_and_b32_e32 v179, 0xffff0000, v210
	v_lshlrev_b32_e32 v180, 16, v211
	v_and_b32_e32 v181, 0xffff0000, v211
	v_add_f32_e32 v174, v174, v178
	v_add_f32_e32 v175, v175, v179
	v_add_f32_e32 v176, v176, v180
	v_add_f32_e32 v177, v177, v181
	v_mfma_f32_32x32x16_bf16 v[2:17], v[118:121], v[150:153], v[2:17]
	v_lshlrev_b32_e32 v178, 16, v212
	v_and_b32_e32 v179, 0xffff0000, v212
	v_lshlrev_b32_e32 v180, 16, v213
	v_and_b32_e32 v181, 0xffff0000, v213
	v_add_f32_e32 v174, v174, v178
	v_add_f32_e32 v175, v175, v179
	v_add_f32_e32 v176, v176, v180
	v_add_f32_e32 v177, v177, v181
	v_lshlrev_b32_e32 v178, 16, v214
	v_and_b32_e32 v179, 0xffff0000, v214
	v_lshlrev_b32_e32 v180, 16, v215
	v_and_b32_e32 v181, 0xffff0000, v215
	v_add_f32_e32 v174, v174, v178
	v_add_f32_e32 v175, v175, v179
	v_add_f32_e32 v176, v176, v180
	v_add_f32_e32 v177, v177, v181
	v_mfma_f32_32x32x16_bf16 v[2:17], v[122:125], v[154:157], v[2:17]
	v_mul_f32_e32 v174, v186, v174
	v_mul_f32_e32 v175, v187, v175
	v_mul_f32_e32 v176, v188, v176
	v_mul_f32_e32 v177, v189, v177
	v_bfe_u32 v178, v174, 16, 1
	v_bfe_u32 v179, v175, 16, 1
	v_bfe_u32 v180, v176, 16, 1
	v_bfe_u32 v181, v177, 16, 1
	v_add3_u32 v174, v174, v178, s23
	v_add3_u32 v175, v175, v179, s23
	v_add3_u32 v176, v176, v180, s23
	v_add3_u32 v177, v177, v181, s23
	global_store_short_d16_hi v197, v174, s[20:21] offset:-4096
	global_store_short_d16_hi v197, v175, s[20:21]
	global_store_short_d16_hi v198, v176, s[20:21] offset:-4096
	global_store_short_d16_hi v198, v177, s[20:21]
	s_add_u32 s20, s20, 0x40000
	s_addc_u32 s21, s21, 0
	v_cvt_pk_bf16_f32 v18, v18, v19
	v_cvt_pk_bf16_f32 v19, v20, v21
	v_cvt_pk_bf16_f32 v20, v22, v23
	v_cvt_pk_bf16_f32 v21, v24, v25
	v_cvt_pk_bf16_f32 v22, v26, v27
	v_cvt_pk_bf16_f32 v23, v28, v29
	v_cvt_pk_bf16_f32 v24, v30, v31
	v_cvt_pk_bf16_f32 v25, v32, v33
	ds_write_b128 v192, v[18:21]
	ds_write_b128 v192, v[22:25] offset:1024
	v_mfma_f32_32x32x16_bf16 v[2:17], v[126:129], v[158:161], v[2:17]
	v_cvt_pk_bf16_f32 v34, v34, v35
	v_cvt_pk_bf16_f32 v35, v36, v37
	v_cvt_pk_bf16_f32 v36, v38, v39
	v_cvt_pk_bf16_f32 v37, v40, v41
	v_cvt_pk_bf16_f32 v38, v42, v43
	v_cvt_pk_bf16_f32 v39, v44, v45
	v_cvt_pk_bf16_f32 v40, v46, v47
	v_cvt_pk_bf16_f32 v41, v48, v49
	ds_write_b128 v192, v[34:37] offset:2048
	ds_write_b128 v192, v[38:41] offset:3072
	v_mfma_f32_32x32x16_bf16 v[2:17], v[130:133], v[162:165], v[2:17]
	s_waitcnt lgkmcnt(0)
	s_barrier
	ds_read2st64_b64 v[200:203], v193 offset0:0 offset1:8
	ds_read2st64_b64 v[204:207], v193 offset0:16 offset1:24
	ds_read2st64_b64 v[208:211], v193 offset0:32 offset1:40
	ds_read2st64_b64 v[212:215], v193 offset0:48 offset1:56
	ds_read_b128 v[150:153], v195 offset:4096
	ds_read_b128 v[154:157], v195 offset:5120
	ds_read_b128 v[158:161], v195 offset:6144
	ds_read_b128 v[162:165], v195 offset:7168
	ds_read_b128 v[166:169], v196 offset:4096
	s_waitcnt vmcnt(9)
	s_andn2_b64 vcc, exec, s[34:35]
	s_cbranch_vccnz .Lp2b_sv_12
	ds_write_b128 v194, v[170:173]
	global_load_dwordx4 v[170:173], v1, s[16:17]
.Lp2b_sv_12:
	global_load_dwordx4 v[118:121], v1, s[14:15]
	global_load_dwordx4 v[122:125], v1, s[14:15] offset:1024
	global_load_dwordx4 v[126:129], v1, s[14:15] offset:2048
	global_load_dwordx4 v[130:133], v1, s[14:15] offset:3072
	v_cvt_pk_bf16_f32 v50, v2, v3
	v_cvt_pk_bf16_f32 v51, v4, v5
	v_cvt_pk_bf16_f32 v52, v6, v7
	v_cvt_pk_bf16_f32 v53, v8, v9
	v_cvt_pk_bf16_f32 v54, v10, v11
	v_cvt_pk_bf16_f32 v55, v12, v13
	v_cvt_pk_bf16_f32 v56, v14, v15
	v_cvt_pk_bf16_f32 v57, v16, v17
	global_load_dwordx4 v[98:101], v1, s[8:9]
	global_load_dwordx4 v[102:105], v1, s[8:9] offset:1024
	global_load_dwordx4 v[106:109], v1, s[8:9] offset:2048
	global_load_dwordx4 v[110:113], v1, s[8:9] offset:3072
	global_load_dwordx4 v[114:117], v1, s[18:19]
	s_waitcnt lgkmcnt(0)
	v_mfma_f32_32x32x16_bf16 v[18:33], v[58:61], v[50:53], 0
	v_mfma_f32_32x32x16_bf16 v[34:49], v[66:69], v[50:53], 0
	v_lshlrev_b32_e32 v178, 16, v200
	v_and_b32_e32 v179, 0xffff0000, v200
	v_lshlrev_b32_e32 v180, 16, v201
	v_and_b32_e32 v181, 0xffff0000, v201
	v_add_f32_e32 v174, 0, v178
	v_add_f32_e32 v175, 0, v179
	v_add_f32_e32 v176, 0, v180
	v_add_f32_e32 v177, 0, v181
	v_lshlrev_b32_e32 v178, 16, v202
	v_and_b32_e32 v179, 0xffff0000, v202
	v_lshlrev_b32_e32 v180, 16, v203
	v_and_b32_e32 v181, 0xffff0000, v203
	v_add_f32_e32 v174, v174, v178
	v_add_f32_e32 v175, v175, v179
	v_add_f32_e32 v176, v176, v180
	v_add_f32_e32 v177, v177, v181
	s_add_u32 s16, s16, 0x8000
	s_addc_u32 s17, s17, 0
	s_add_u32 s14, s14, 0x8000
	s_addc_u32 s15, s15, 0
	s_add_u32 s8, s8, 0x8000
	s_addc_u32 s9, s9, 0
	s_add_u32 s18, s18, 0x2000
	s_addc_u32 s19, s19, 0
	v_mfma_f32_32x32x16_bf16 v[18:33], v[62:65], v[54:57], v[18:33]
	v_mfma_f32_32x32x16_bf16 v[34:49], v[70:73], v[54:57], v[34:49]
	v_lshlrev_b32_e32 v178, 16, v204
	v_and_b32_e32 v179, 0xffff0000, v204
	v_lshlrev_b32_e32 v180, 16, v205
	v_and_b32_e32 v181, 0xffff0000, v205
	v_add_f32_e32 v174, v174, v178
	v_add_f32_e32 v175, v175, v179
	v_add_f32_e32 v176, v176, v180
	v_add_f32_e32 v177, v177, v181
	v_lshlrev_b32_e32 v178, 16, v206
	v_and_b32_e32 v179, 0xffff0000, v206
	v_lshlrev_b32_e32 v180, 16, v207
	v_and_b32_e32 v181, 0xffff0000, v207
	v_add_f32_e32 v174, v174, v178
	v_add_f32_e32 v175, v175, v179
	v_add_f32_e32 v176, v176, v180
	v_add_f32_e32 v177, v177, v181
	v_mul_f32_e32 v2, v190, v2
	v_mul_f32_e32 v3, v190, v3
	v_mul_f32_e32 v4, v190, v4
	v_mul_f32_e32 v5, v190, v5
	v_mul_f32_e32 v6, v190, v6
	v_mul_f32_e32 v7, v190, v7
	v_mul_f32_e32 v8, v190, v8
	v_mul_f32_e32 v9, v190, v9
	v_mul_f32_e32 v10, v190, v10
	v_mul_f32_e32 v11, v190, v11
	v_mul_f32_e32 v12, v190, v12
	v_mul_f32_e32 v13, v190, v13
	v_mul_f32_e32 v14, v190, v14
	v_mul_f32_e32 v15, v190, v15
	v_mul_f32_e32 v16, v190, v16
	v_mul_f32_e32 v17, v190, v17
	s_cmp_eq_u32 s7, 0
	s_cbranch_scc0 .Lp2b_in_13
	v_mfma_f32_32x32x16_bf16 v[18:33], v[74:77], v[166:169], v[18:33]
	s_branch .Lp2b_in_14

.Lp2b_sv_15:
	global_load_dwordx4 v[134:137], v1, s[14:15]
	global_load_dwordx4 v[138:141], v1, s[14:15] offset:1024
	global_load_dwordx4 v[142:145], v1, s[14:15] offset:2048
	global_load_dwordx4 v[146:149], v1, s[14:15] offset:3072
	v_cvt_pk_bf16_f32 v50, v2, v3
	v_cvt_pk_bf16_f32 v51, v4, v5
	v_cvt_pk_bf16_f32 v52, v6, v7
	v_cvt_pk_bf16_f32 v53, v8, v9
	v_cvt_pk_bf16_f32 v54, v10, v11
	v_cvt_pk_bf16_f32 v55, v12, v13
	v_cvt_pk_bf16_f32 v56, v14, v15
	v_cvt_pk_bf16_f32 v57, v16, v17
	global_load_dwordx4 v[58:61], v1, s[8:9]
	global_load_dwordx4 v[62:65], v1, s[8:9] offset:1024
	global_load_dwordx4 v[66:69], v1, s[8:9] offset:2048
	global_load_dwordx4 v[70:73], v1, s[8:9] offset:3072
	global_load_dwordx4 v[74:77], v1, s[18:19]
	s_waitcnt lgkmcnt(0)
	v_mfma_f32_32x32x16_bf16 v[18:33], v[78:81], v[50:53], 0
	v_mfma_f32_32x32x16_bf16 v[34:49], v[86:89], v[50:53], 0
	v_lshlrev_b32_e32 v178, 16, v200
	v_and_b32_e32 v179, 0xffff0000, v200
	v_lshlrev_b32_e32 v180, 16, v201
	v_and_b32_e32 v181, 0xffff0000, v201
	v_add_f32_e32 v174, 0, v178
	v_add_f32_e32 v175, 0, v179
	v_add_f32_e32 v176, 0, v180
	v_add_f32_e32 v177, 0, v181
	v_lshlrev_b32_e32 v178, 16, v202
	v_and_b32_e32 v179, 0xffff0000, v202
	v_lshlrev_b32_e32 v180, 16, v203
	v_and_b32_e32 v181, 0xffff0000, v203
	v_add_f32_e32 v174, v174, v178
	v_add_f32_e32 v175, v175, v179
	v_add_f32_e32 v176, v176, v180
	v_add_f32_e32 v177, v177, v181
	s_add_u32 s16, s16, 0x8000
	s_addc_u32 s17, s17, 0
	s_add_u32 s14, s14, 0x8000
	s_addc_u32 s15, s15, 0
	s_add_u32 s8, s8, 0x8000
	s_addc_u32 s9, s9, 0
	s_add_u32 s18, s18, 0x2000
	s_addc_u32 s19, s19, 0
	v_mfma_f32_32x32x16_bf16 v[18:33], v[82:85], v[54:57], v[18:33]
	v_mfma_f32_32x32x16_bf16 v[34:49], v[90:93], v[54:57], v[34:49]
	v_lshlrev_b32_e32 v178, 16, v204
	v_and_b32_e32 v179, 0xffff0000, v204
	v_lshlrev_b32_e32 v180, 16, v205
	v_and_b32_e32 v181, 0xffff0000, v205
	v_add_f32_e32 v174, v174, v178
	v_add_f32_e32 v175, v175, v179
	v_add_f32_e32 v176, v176, v180
	v_add_f32_e32 v177, v177, v181
	v_lshlrev_b32_e32 v178, 16, v206
	v_and_b32_e32 v179, 0xffff0000, v206
	v_lshlrev_b32_e32 v180, 16, v207
	v_and_b32_e32 v181, 0xffff0000, v207
	v_add_f32_e32 v174, v174, v178
	v_add_f32_e32 v175, v175, v179
	v_add_f32_e32 v176, v176, v180
	v_add_f32_e32 v177, v177, v181
	v_mul_f32_e32 v2, v190, v2
	v_mul_f32_e32 v3, v190, v3
	v_mul_f32_e32 v4, v190, v4
	v_mul_f32_e32 v5, v190, v5
	v_mul_f32_e32 v6, v190, v6
	v_mul_f32_e32 v7, v190, v7
	v_mul_f32_e32 v8, v190, v8
	v_mul_f32_e32 v9, v190, v9
	v_mul_f32_e32 v10, v190, v10
	v_mul_f32_e32 v11, v190, v11
	v_mul_f32_e32 v12, v190, v12
	v_mul_f32_e32 v13, v190, v13
	v_mul_f32_e32 v14, v190, v14
	v_mul_f32_e32 v15, v190, v15
	v_mul_f32_e32 v16, v190, v16
	v_mul_f32_e32 v17, v190, v17
	s_cmp_eq_u32 s7, 0
	s_cbranch_scc0 .Lp2b_in_16
	v_mfma_f32_32x32x16_bf16 v[18:33], v[94:97], v[166:169], v[18:33]
	s_branch .Lp2b_in_17

.Lp2b_sv_18:
	global_load_dwordx4 v[118:121], v1, s[14:15]
	global_load_dwordx4 v[122:125], v1, s[14:15] offset:1024
	global_load_dwordx4 v[126:129], v1, s[14:15] offset:2048
	global_load_dwordx4 v[130:133], v1, s[14:15] offset:3072
	v_cvt_pk_bf16_f32 v50, v2, v3
	v_cvt_pk_bf16_f32 v51, v4, v5
	v_cvt_pk_bf16_f32 v52, v6, v7
	v_cvt_pk_bf16_f32 v53, v8, v9
	v_cvt_pk_bf16_f32 v54, v10, v11
	v_cvt_pk_bf16_f32 v55, v12, v13
	v_cvt_pk_bf16_f32 v56, v14, v15
	v_cvt_pk_bf16_f32 v57, v16, v17
	global_load_dwordx4 v[78:81], v1, s[8:9]
	global_load_dwordx4 v[82:85], v1, s[8:9] offset:1024
	global_load_dwordx4 v[86:89], v1, s[8:9] offset:2048
	global_load_dwordx4 v[90:93], v1, s[8:9] offset:3072
	global_load_dwordx4 v[94:97], v1, s[18:19]
	s_waitcnt lgkmcnt(0)
	v_mfma_f32_32x32x16_bf16 v[18:33], v[98:101], v[50:53], 0
	v_mfma_f32_32x32x16_bf16 v[34:49], v[106:109], v[50:53], 0
	v_lshlrev_b32_e32 v178, 16, v200
	v_and_b32_e32 v179, 0xffff0000, v200
	v_lshlrev_b32_e32 v180, 16, v201
	v_and_b32_e32 v181, 0xffff0000, v201
	v_add_f32_e32 v174, 0, v178
	v_add_f32_e32 v175, 0, v179
	v_add_f32_e32 v176, 0, v180
	v_add_f32_e32 v177, 0, v181
	v_lshlrev_b32_e32 v178, 16, v202
	v_and_b32_e32 v179, 0xffff0000, v202
	v_lshlrev_b32_e32 v180, 16, v203
	v_and_b32_e32 v181, 0xffff0000, v203
	v_add_f32_e32 v174, v174, v178
	v_add_f32_e32 v175, v175, v179
	v_add_f32_e32 v176, v176, v180
	v_add_f32_e32 v177, v177, v181
	s_add_u32 s16, s16, 0x8000
	s_addc_u32 s17, s17, 0
	s_add_u32 s14, s14, 0x8000
	s_addc_u32 s15, s15, 0
	s_add_u32 s8, s8, 0x8000
	s_addc_u32 s9, s9, 0
	s_add_u32 s18, s18, 0x2000
	s_addc_u32 s19, s19, 0
	v_mfma_f32_32x32x16_bf16 v[18:33], v[102:105], v[54:57], v[18:33]
	v_mfma_f32_32x32x16_bf16 v[34:49], v[110:113], v[54:57], v[34:49]
	v_lshlrev_b32_e32 v178, 16, v204
	v_and_b32_e32 v179, 0xffff0000, v204
	v_lshlrev_b32_e32 v180, 16, v205
	v_and_b32_e32 v181, 0xffff0000, v205
	v_add_f32_e32 v174, v174, v178
	v_add_f32_e32 v175, v175, v179
	v_add_f32_e32 v176, v176, v180
	v_add_f32_e32 v177, v177, v181
	v_lshlrev_b32_e32 v178, 16, v206
	v_and_b32_e32 v179, 0xffff0000, v206
	v_lshlrev_b32_e32 v180, 16, v207
	v_and_b32_e32 v181, 0xffff0000, v207
	v_add_f32_e32 v174, v174, v178
	v_add_f32_e32 v175, v175, v179
	v_add_f32_e32 v176, v176, v180
	v_add_f32_e32 v177, v177, v181
	v_mul_f32_e32 v2, v190, v2
	v_mul_f32_e32 v3, v190, v3
	v_mul_f32_e32 v4, v190, v4
	v_mul_f32_e32 v5, v190, v5
	v_mul_f32_e32 v6, v190, v6
	v_mul_f32_e32 v7, v190, v7
	v_mul_f32_e32 v8, v190, v8
	v_mul_f32_e32 v9, v190, v9
	v_mul_f32_e32 v10, v190, v10
	v_mul_f32_e32 v11, v190, v11
	v_mul_f32_e32 v12, v190, v12
	v_mul_f32_e32 v13, v190, v13
	v_mul_f32_e32 v14, v190, v14
	v_mul_f32_e32 v15, v190, v15
	v_mul_f32_e32 v16, v190, v16
	v_mul_f32_e32 v17, v190, v17
	s_cmp_eq_u32 s7, 0
	s_cbranch_scc0 .Lp2b_in_19
	v_mfma_f32_32x32x16_bf16 v[18:33], v[114:117], v[166:169], v[18:33]
	s_branch .Lp2b_in_20

.Lp2b_sv_21:
	global_load_dwordx4 v[134:137], v1, s[14:15]
	global_load_dwordx4 v[138:141], v1, s[14:15] offset:1024
	global_load_dwordx4 v[142:145], v1, s[14:15] offset:2048
	global_load_dwordx4 v[146:149], v1, s[14:15] offset:3072
	v_cvt_pk_bf16_f32 v50, v2, v3
	v_cvt_pk_bf16_f32 v51, v4, v5
	v_cvt_pk_bf16_f32 v52, v6, v7
	v_cvt_pk_bf16_f32 v53, v8, v9
	v_cvt_pk_bf16_f32 v54, v10, v11
	v_cvt_pk_bf16_f32 v55, v12, v13
	v_cvt_pk_bf16_f32 v56, v14, v15
	v_cvt_pk_bf16_f32 v57, v16, v17
	global_load_dwordx4 v[98:101], v1, s[8:9]
	global_load_dwordx4 v[102:105], v1, s[8:9] offset:1024
	global_load_dwordx4 v[106:109], v1, s[8:9] offset:2048
	global_load_dwordx4 v[110:113], v1, s[8:9] offset:3072
	global_load_dwordx4 v[114:117], v1, s[18:19]
	s_waitcnt lgkmcnt(0)
	v_mfma_f32_32x32x16_bf16 v[18:33], v[58:61], v[50:53], 0
	v_mfma_f32_32x32x16_bf16 v[34:49], v[66:69], v[50:53], 0
	v_lshlrev_b32_e32 v178, 16, v200
	v_and_b32_e32 v179, 0xffff0000, v200
	v_lshlrev_b32_e32 v180, 16, v201
	v_and_b32_e32 v181, 0xffff0000, v201
	v_add_f32_e32 v174, 0, v178
	v_add_f32_e32 v175, 0, v179
	v_add_f32_e32 v176, 0, v180
	v_add_f32_e32 v177, 0, v181
	v_lshlrev_b32_e32 v178, 16, v202
	v_and_b32_e32 v179, 0xffff0000, v202
	v_lshlrev_b32_e32 v180, 16, v203
	v_and_b32_e32 v181, 0xffff0000, v203
	v_add_f32_e32 v174, v174, v178
	v_add_f32_e32 v175, v175, v179
	v_add_f32_e32 v176, v176, v180
	v_add_f32_e32 v177, v177, v181
	s_add_u32 s16, s16, 0x8000
	s_addc_u32 s17, s17, 0
	s_add_u32 s14, s14, 0x8000
	s_addc_u32 s15, s15, 0
	s_add_u32 s8, s8, 0x8000
	s_addc_u32 s9, s9, 0
	s_add_u32 s18, s18, 0x2000
	s_addc_u32 s19, s19, 0
	v_mfma_f32_32x32x16_bf16 v[18:33], v[62:65], v[54:57], v[18:33]
	v_mfma_f32_32x32x16_bf16 v[34:49], v[70:73], v[54:57], v[34:49]
	v_lshlrev_b32_e32 v178, 16, v204
	v_and_b32_e32 v179, 0xffff0000, v204
	v_lshlrev_b32_e32 v180, 16, v205
	v_and_b32_e32 v181, 0xffff0000, v205
	v_add_f32_e32 v174, v174, v178
	v_add_f32_e32 v175, v175, v179
	v_add_f32_e32 v176, v176, v180
	v_add_f32_e32 v177, v177, v181
	v_lshlrev_b32_e32 v178, 16, v206
	v_and_b32_e32 v179, 0xffff0000, v206
	v_lshlrev_b32_e32 v180, 16, v207
	v_and_b32_e32 v181, 0xffff0000, v207
	v_add_f32_e32 v174, v174, v178
	v_add_f32_e32 v175, v175, v179
	v_add_f32_e32 v176, v176, v180
	v_add_f32_e32 v177, v177, v181
	v_mul_f32_e32 v2, v190, v2
	v_mul_f32_e32 v3, v190, v3
	v_mul_f32_e32 v4, v190, v4
	v_mul_f32_e32 v5, v190, v5
	v_mul_f32_e32 v6, v190, v6
	v_mul_f32_e32 v7, v190, v7
	v_mul_f32_e32 v8, v190, v8
	v_mul_f32_e32 v9, v190, v9
	v_mul_f32_e32 v10, v190, v10
	v_mul_f32_e32 v11, v190, v11
	v_mul_f32_e32 v12, v190, v12
	v_mul_f32_e32 v13, v190, v13
	v_mul_f32_e32 v14, v190, v14
	v_mul_f32_e32 v15, v190, v15
	v_mul_f32_e32 v16, v190, v16
	v_mul_f32_e32 v17, v190, v17
	s_cmp_eq_u32 s7, 0
	s_cbranch_scc0 .Lp2b_in_22
	v_mfma_f32_32x32x16_bf16 v[18:33], v[74:77], v[166:169], v[18:33]
	s_branch .Lp2b_in_23

; __device__ __forceinline__ void scan_phase(const bf16* q, const bf16* kdT, const bf16* vT, const bf16* Pp, bf16* o, LAS unsigned char* lds, int bid, int G, int wave, int lane, int tid) {
;     ...
;         for (int i = 0; i < 60; i += 6) { SCAN_STEP(0, 2, 0, 1, i); SCAN_STEP(1, 0, 1, 0, i + 1); SCAN_STEP(2, 1, 0, 1, i + 2); SCAN_STEP(0, 2, 1, 0, i + 3); SCAN_STEP(1, 0, 0, 1, i + 4); SCAN_STEP(2, 1, 1, 0, i + 5); }
.Lp2b_in_23:
	v_lshlrev_b32_e32 v178, 16, v208
	v_and_b32_e32 v179, 0xffff0000, v208
	v_lshlrev_b32_e32 v180, 16, v209
	v_and_b32_e32 v181, 0xffff0000, v209
	v_add_f32_e32 v174, v174, v178
	v_add_f32_e32 v175, v175, v179
	v_add_f32_e32 v176, v176, v180
	v_add_f32_e32 v177, v177, v181
	v_lshlrev_b32_e32 v178, 16, v210
	v_and_b32_e32 v179, 0xffff0000, v210
	v_lshlrev_b32_e32 v180, 16, v211
	v_and_b32_e32 v181, 0xffff0000, v211
	v_add_f32_e32 v174, v174, v178
	v_add_f32_e32 v175, v175, v179
	v_add_f32_e32 v176, v176, v180
	v_add_f32_e32 v177, v177, v181
	v_mfma_f32_32x32x16_bf16 v[2:17], v[118:121], v[150:153], v[2:17]
	v_lshlrev_b32_e32 v178, 16, v212
	v_and_b32_e32 v179, 0xffff0000, v212
	v_lshlrev_b32_e32 v180, 16, v213
	v_and_b32_e32 v181, 0xffff0000, v213
	v_add_f32_e32 v174, v174, v178
	v_add_f32_e32 v175, v175, v179
	v_add_f32_e32 v176, v176, v180
	v_add_f32_e32 v177, v177, v181
	v_lshlrev_b32_e32 v178, 16, v214
	v_and_b32_e32 v179, 0xffff0000, v214
	v_lshlrev_b32_e32 v180, 16, v215
	v_and_b32_e32 v181, 0xffff0000, v215
	v_add_f32_e32 v174, v174, v178
	v_add_f32_e32 v175, v175, v179
	v_add_f32_e32 v176, v176, v180
	v_add_f32_e32 v177, v177, v181
	v_mfma_f32_32x32x16_bf16 v[2:17], v[122:125], v[154:157], v[2:17]
	v_mul_f32_e32 v174, v186, v174
	v_mul_f32_e32 v175, v187, v175
	v_mul_f32_e32 v176, v188, v176
	v_mul_f32_e32 v177, v189, v177
	v_bfe_u32 v178, v174, 16, 1
	v_bfe_u32 v179, v175, 16, 1
	v_bfe_u32 v180, v176, 16, 1
	v_bfe_u32 v181, v177, 16, 1
	v_add3_u32 v174, v174, v178, s23
	v_add3_u32 v175, v175, v179, s23
	v_add3_u32 v176, v176, v180, s23
	v_add3_u32 v177, v177, v181, s23
	global_store_short_d16_hi v197, v174, s[20:21] offset:-4096
	global_store_short_d16_hi v197, v175, s[20:21]
	global_store_short_d16_hi v198, v176, s[20:21] offset:-4096
	global_store_short_d16_hi v198, v177, s[20:21]
	s_add_u32 s20, s20, 0x40000
	s_addc_u32 s21, s21, 0
	v_cvt_pk_bf16_f32 v18, v18, v19
	v_cvt_pk_bf16_f32 v19, v20, v21
	v_cvt_pk_bf16_f32 v20, v22, v23
	v_cvt_pk_bf16_f32 v21, v24, v25
	v_cvt_pk_bf16_f32 v22, v26, v27
	v_cvt_pk_bf16_f32 v23, v28, v29
	v_cvt_pk_bf16_f32 v24, v30, v31
	v_cvt_pk_bf16_f32 v25, v32, v33
	ds_write_b128 v192, v[18:21]
	ds_write_b128 v192, v[22:25] offset:1024
	v_mfma_f32_32x32x16_bf16 v[2:17], v[126:129], v[158:161], v[2:17]
	v_cvt_pk_bf16_f32 v34, v34, v35
	v_cvt_pk_bf16_f32 v35, v36, v37
	v_cvt_pk_bf16_f32 v36, v38, v39
	v_cvt_pk_bf16_f32 v37, v40, v41
	v_cvt_pk_bf16_f32 v38, v42, v43
	v_cvt_pk_bf16_f32 v39, v44, v45
	v_cvt_pk_bf16_f32 v40, v46, v47
	v_cvt_pk_bf16_f32 v41, v48, v49
	ds_write_b128 v192, v[34:37] offset:2048
	ds_write_b128 v192, v[38:41] offset:3072
	v_mfma_f32_32x32x16_bf16 v[2:17], v[130:133], v[162:165], v[2:17]
	s_waitcnt lgkmcnt(0)
	s_barrier
	ds_read2st64_b64 v[200:203], v193 offset0:0 offset1:8
	ds_read2st64_b64 v[204:207], v193 offset0:16 offset1:24
	ds_read2st64_b64 v[208:211], v193 offset0:32 offset1:40
	ds_read2st64_b64 v[212:215], v193 offset0:48 offset1:56
	ds_read_b128 v[150:153], v195 offset:4096
	ds_read_b128 v[154:157], v195 offset:5120
	ds_read_b128 v[158:161], v195 offset:6144
	ds_read_b128 v[162:165], v195 offset:7168
	ds_read_b128 v[166:169], v196 offset:4096
	s_add_i32 s22, s22, 1
	s_cmp_lt_u32 s22, 10
	s_cbranch_scc1 .Lp2b_loop
	s_waitcnt vmcnt(9)
	s_andn2_b64 vcc, exec, s[34:35]
	s_cbranch_vccnz .Lp2b_sv_24
	ds_write_b128 v194, v[170:173]
	global_load_dwordx4 v[170:173], v1, s[16:17]

; __device__ __forceinline__ void scan_phase(const bf16* q, const bf16* kdT, const bf16* vT, const bf16* Pp, bf16* o, LAS unsigned char* lds, int bid, int G, int wave, int lane, int tid) {
;     ...
;         SCAN_STEP(0, 2, 0, 1, 60); SCAN_STEP(1, 0, 1, 0, 61); SCAN_STEP(2, 1, 0, 1, 62); SCAN_STEP(0, 2, 1, 0, 63);
.Lp2b_in_26:
	v_lshlrev_b32_e32 v178, 16, v208
	v_and_b32_e32 v179, 0xffff0000, v208
	v_lshlrev_b32_e32 v180, 16, v209
	v_and_b32_e32 v181, 0xffff0000, v209
	v_add_f32_e32 v174, v174, v178
	v_add_f32_e32 v175, v175, v179
	v_add_f32_e32 v176, v176, v180
	v_add_f32_e32 v177, v177, v181
	v_lshlrev_b32_e32 v178, 16, v210
	v_and_b32_e32 v179, 0xffff0000, v210
	v_lshlrev_b32_e32 v180, 16, v211
	v_and_b32_e32 v181, 0xffff0000, v211
	v_add_f32_e32 v174, v174, v178
	v_add_f32_e32 v175, v175, v179
	v_add_f32_e32 v176, v176, v180
	v_add_f32_e32 v177, v177, v181
	v_mfma_f32_32x32x16_bf16 v[2:17], v[134:137], v[150:153], v[2:17]
	v_lshlrev_b32_e32 v178, 16, v212
	v_and_b32_e32 v179, 0xffff0000, v212
	v_lshlrev_b32_e32 v180, 16, v213
	v_and_b32_e32 v181, 0xffff0000, v213
	v_add_f32_e32 v174, v174, v178
	v_add_f32_e32 v175, v175, v179
	v_add_f32_e32 v176, v176, v180
	v_add_f32_e32 v177, v177, v181
	v_lshlrev_b32_e32 v178, 16, v214
	v_and_b32_e32 v179, 0xffff0000, v214
	v_lshlrev_b32_e32 v180, 16, v215
	v_and_b32_e32 v181, 0xffff0000, v215
	v_add_f32_e32 v174, v174, v178
	v_add_f32_e32 v175, v175, v179
	v_add_f32_e32 v176, v176, v180
	v_add_f32_e32 v177, v177, v181
	v_mfma_f32_32x32x16_bf16 v[2:17], v[138:141], v[154:157], v[2:17]
	v_mul_f32_e32 v174, v186, v174
	v_mul_f32_e32 v175, v187, v175
	v_mul_f32_e32 v176, v188, v176
	v_mul_f32_e32 v177, v189, v177
	v_bfe_u32 v178, v174, 16, 1
	v_bfe_u32 v179, v175, 16, 1
	v_bfe_u32 v180, v176, 16, 1
	v_bfe_u32 v181, v177, 16, 1
	v_add3_u32 v174, v174, v178, s23
	v_add3_u32 v175, v175, v179, s23
	v_add3_u32 v176, v176, v180, s23
	v_add3_u32 v177, v177, v181, s23
	global_store_short_d16_hi v197, v174, s[20:21] offset:-4096
	global_store_short_d16_hi v197, v175, s[20:21]
	global_store_short_d16_hi v198, v176, s[20:21] offset:-4096
	global_store_short_d16_hi v198, v177, s[20:21]
	s_add_u32 s20, s20, 0x40000
	s_addc_u32 s21, s21, 0
	v_cvt_pk_bf16_f32 v18, v18, v19
	v_cvt_pk_bf16_f32 v19, v20, v21
	v_cvt_pk_bf16_f32 v20, v22, v23
	v_cvt_pk_bf16_f32 v21, v24, v25
	v_cvt_pk_bf16_f32 v22, v26, v27
	v_cvt_pk_bf16_f32 v23, v28, v29
	v_cvt_pk_bf16_f32 v24, v30, v31
	v_cvt_pk_bf16_f32 v25, v32, v33
	ds_write_b128 v192, v[18:21] offset:32768
	ds_write_b128 v192, v[22:25] offset:33792
	v_mfma_f32_32x32x16_bf16 v[2:17], v[142:145], v[158:161], v[2:17]
	v_cvt_pk_bf16_f32 v34, v34, v35
	v_cvt_pk_bf16_f32 v35, v36, v37
	v_cvt_pk_bf16_f32 v36, v38, v39
	v_cvt_pk_bf16_f32 v37, v40, v41
	v_cvt_pk_bf16_f32 v38, v42, v43
	v_cvt_pk_bf16_f32 v39, v44, v45
	v_cvt_pk_bf16_f32 v40, v46, v47
	v_cvt_pk_bf16_f32 v41, v48, v49
	ds_write_b128 v192, v[34:37] offset:34816
	ds_write_b128 v192, v[38:41] offset:35840
	v_mfma_f32_32x32x16_bf16 v[2:17], v[146:149], v[162:165], v[2:17]
	s_waitcnt lgkmcnt(0)
	s_barrier
	ds_read2st64_b64 v[200:203], v193 offset0:64 offset1:72
	ds_read2st64_b64 v[204:207], v193 offset0:80 offset1:88
	ds_read2st64_b64 v[208:211], v193 offset0:96 offset1:104
	ds_read2st64_b64 v[212:215], v193 offset0:112 offset1:120
	ds_read_b128 v[150:153], v195
	ds_read_b128 v[154:157], v195 offset:1024
	ds_read_b128 v[158:161], v195 offset:2048
	ds_read_b128 v[162:165], v195 offset:3072
	ds_read_b128 v[166:169], v196
	s_waitcnt vmcnt(9)
	s_andn2_b64 vcc, exec, s[34:35]
	s_cbranch_vccnz .Lp2b_sv_27
	ds_write_b128 v194, v[170:173] offset:4096
.Lp2b_sv_27:
	global_load_dwordx4 v[134:137], v1, s[14:15]
	global_load_dwordx4 v[138:141], v1, s[14:15] offset:1024
	global_load_dwordx4 v[142:145], v1, s[14:15] offset:2048
	global_load_dwordx4 v[146:149], v1, s[14:15] offset:3072
	v_cvt_pk_bf16_f32 v50, v2, v3
	v_cvt_pk_bf16_f32 v51, v4, v5
	v_cvt_pk_bf16_f32 v52, v6, v7
	v_cvt_pk_bf16_f32 v53, v8, v9
	v_cvt_pk_bf16_f32 v54, v10, v11
	v_cvt_pk_bf16_f32 v55, v12, v13
	v_cvt_pk_bf16_f32 v56, v14, v15
	v_cvt_pk_bf16_f32 v57, v16, v17
	s_waitcnt lgkmcnt(0)
	v_mfma_f32_32x32x16_bf16 v[18:33], v[98:101], v[50:53], 0
	v_mfma_f32_32x32x16_bf16 v[34:49], v[106:109], v[50:53], 0
	v_lshlrev_b32_e32 v178, 16, v200
	v_and_b32_e32 v179, 0xffff0000, v200
	v_lshlrev_b32_e32 v180, 16, v201
	v_and_b32_e32 v181, 0xffff0000, v201
	v_add_f32_e32 v174, 0, v178
	v_add_f32_e32 v175, 0, v179
	v_add_f32_e32 v176, 0, v180
	v_add_f32_e32 v177, 0, v181
	v_lshlrev_b32_e32 v178, 16, v202
	v_and_b32_e32 v179, 0xffff0000, v202
	v_lshlrev_b32_e32 v180, 16, v203
	v_and_b32_e32 v181, 0xffff0000, v203
	v_add_f32_e32 v174, v174, v178
	v_add_f32_e32 v175, v175, v179
	v_add_f32_e32 v176, v176, v180
	v_add_f32_e32 v177, v177, v181
	s_add_u32 s14, s14, 0x8000
	s_addc_u32 s15, s15, 0
	v_mfma_f32_32x32x16_bf16 v[18:33], v[102:105], v[54:57], v[18:33]
	v_mfma_f32_32x32x16_bf16 v[34:49], v[110:113], v[54:57], v[34:49]
	v_lshlrev_b32_e32 v178, 16, v204
	v_and_b32_e32 v179, 0xffff0000, v204
	v_lshlrev_b32_e32 v180, 16, v205
	v_and_b32_e32 v181, 0xffff0000, v205
	v_add_f32_e32 v174, v174, v178
	v_add_f32_e32 v175, v175, v179
	v_add_f32_e32 v176, v176, v180
	v_add_f32_e32 v177, v177, v181
	v_lshlrev_b32_e32 v178, 16, v206
	v_and_b32_e32 v179, 0xffff0000, v206
	v_lshlrev_b32_e32 v180, 16, v207
	v_and_b32_e32 v181, 0xffff0000, v207
	v_add_f32_e32 v174, v174, v178
	v_add_f32_e32 v175, v175, v179
	v_add_f32_e32 v176, v176, v180
	v_add_f32_e32 v177, v177, v181
	v_mul_f32_e32 v2, v190, v2
	v_mul_f32_e32 v3, v190, v3
	v_mul_f32_e32 v4, v190, v4
	v_mul_f32_e32 v5, v190, v5
	v_mul_f32_e32 v6, v190, v6
	v_mul_f32_e32 v7, v190, v7
	v_mul_f32_e32 v8, v190, v8
	v_mul_f32_e32 v9, v190, v9
	v_mul_f32_e32 v10, v190, v10
	v_mul_f32_e32 v11, v190, v11
	v_mul_f32_e32 v12, v190, v12
	v_mul_f32_e32 v13, v190, v13
	v_mul_f32_e32 v14, v190, v14
	v_mul_f32_e32 v15, v190, v15
	v_mul_f32_e32 v16, v190, v16
	v_mul_f32_e32 v17, v190, v17
	s_cmp_eq_u32 s7, 0
	s_cbranch_scc0 .Lp2b_in_28
	v_mfma_f32_32x32x16_bf16 v[18:33], v[114:117], v[166:169], v[18:33]
	s_branch .Lp2b_in_29

; __device__ __forceinline__ void scan_phase(const bf16* q, const bf16* kdT, const bf16* vT, const bf16* Pp, bf16* o, LAS unsigned char* lds, int bid, int G, int wave, int lane, int tid) {
;     ...
;         SCAN_STEP(0, 2, 0, 1, 60); SCAN_STEP(1, 0, 1, 0, 61); SCAN_STEP(2, 1, 0, 1, 62); SCAN_STEP(0, 2, 1, 0, 63);
.Lp2b_in_29:
	v_lshlrev_b32_e32 v178, 16, v208
	v_and_b32_e32 v179, 0xffff0000, v208
	v_lshlrev_b32_e32 v180, 16, v209
	v_and_b32_e32 v181, 0xffff0000, v209
	v_add_f32_e32 v174, v174, v178
	v_add_f32_e32 v175, v175, v179
	v_add_f32_e32 v176, v176, v180
	v_add_f32_e32 v177, v177, v181
	v_lshlrev_b32_e32 v178, 16, v210
	v_and_b32_e32 v179, 0xffff0000, v210
	v_lshlrev_b32_e32 v180, 16, v211
	v_and_b32_e32 v181, 0xffff0000, v211
	v_add_f32_e32 v174, v174, v178
	v_add_f32_e32 v175, v175, v179
	v_add_f32_e32 v176, v176, v180
	v_add_f32_e32 v177, v177, v181
	v_mfma_f32_32x32x16_bf16 v[2:17], v[118:121], v[150:153], v[2:17]
	v_lshlrev_b32_e32 v178, 16, v212
	v_and_b32_e32 v179, 0xffff0000, v212
	v_lshlrev_b32_e32 v180, 16, v213
	v_and_b32_e32 v181, 0xffff0000, v213
	v_add_f32_e32 v174, v174, v178
	v_add_f32_e32 v175, v175, v179
	v_add_f32_e32 v176, v176, v180
	v_add_f32_e32 v177, v177, v181
	v_lshlrev_b32_e32 v178, 16, v214
	v_and_b32_e32 v179, 0xffff0000, v214
	v_lshlrev_b32_e32 v180, 16, v215
	v_and_b32_e32 v181, 0xffff0000, v215
	v_add_f32_e32 v174, v174, v178
	v_add_f32_e32 v175, v175, v179
	v_add_f32_e32 v176, v176, v180
	v_add_f32_e32 v177, v177, v181
	v_mfma_f32_32x32x16_bf16 v[2:17], v[122:125], v[154:157], v[2:17]
	v_mul_f32_e32 v174, v186, v174
	v_mul_f32_e32 v175, v187, v175
	v_mul_f32_e32 v176, v188, v176
	v_mul_f32_e32 v177, v189, v177
	v_bfe_u32 v178, v174, 16, 1
	v_bfe_u32 v179, v175, 16, 1
	v_bfe_u32 v180, v176, 16, 1
	v_bfe_u32 v181, v177, 16, 1
	v_add3_u32 v174, v174, v178, s23
	v_add3_u32 v175, v175, v179, s23
	v_add3_u32 v176, v176, v180, s23
	v_add3_u32 v177, v177, v181, s23
	global_store_short_d16_hi v197, v174, s[20:21] offset:-4096
	global_store_short_d16_hi v197, v175, s[20:21]
	global_store_short_d16_hi v198, v176, s[20:21] offset:-4096
	global_store_short_d16_hi v198, v177, s[20:21]
	s_add_u32 s20, s20, 0x40000
	s_addc_u32 s21, s21, 0
	v_cvt_pk_bf16_f32 v18, v18, v19
	v_cvt_pk_bf16_f32 v19, v20, v21
	v_cvt_pk_bf16_f32 v20, v22, v23
	v_cvt_pk_bf16_f32 v21, v24, v25
	v_cvt_pk_bf16_f32 v22, v26, v27
	v_cvt_pk_bf16_f32 v23, v28, v29
	v_cvt_pk_bf16_f32 v24, v30, v31
	v_cvt_pk_bf16_f32 v25, v32, v33
	ds_write_b128 v192, v[18:21]
	ds_write_b128 v192, v[22:25] offset:1024
	v_mfma_f32_32x32x16_bf16 v[2:17], v[126:129], v[158:161], v[2:17]
	v_cvt_pk_bf16_f32 v34, v34, v35
	v_cvt_pk_bf16_f32 v35, v36, v37
	v_cvt_pk_bf16_f32 v36, v38, v39
	v_cvt_pk_bf16_f32 v37, v40, v41
	v_cvt_pk_bf16_f32 v38, v42, v43
	v_cvt_pk_bf16_f32 v39, v44, v45
	v_cvt_pk_bf16_f32 v40, v46, v47
	v_cvt_pk_bf16_f32 v41, v48, v49
	ds_write_b128 v192, v[34:37] offset:2048
	ds_write_b128 v192, v[38:41] offset:3072
	v_mfma_f32_32x32x16_bf16 v[2:17], v[130:133], v[162:165], v[2:17]
	s_waitcnt lgkmcnt(0)
	s_barrier
	ds_read2st64_b64 v[200:203], v193 offset0:0 offset1:8
	ds_read2st64_b64 v[204:207], v193 offset0:16 offset1:24
	ds_read2st64_b64 v[208:211], v193 offset0:32 offset1:40
	ds_read2st64_b64 v[212:215], v193 offset0:48 offset1:56
	ds_read_b128 v[150:153], v195 offset:4096
	ds_read_b128 v[154:157], v195 offset:5120
	ds_read_b128 v[158:161], v195 offset:6144
	ds_read_b128 v[162:165], v195 offset:7168
	ds_read_b128 v[166:169], v196 offset:4096
	s_waitcnt vmcnt(4)
	v_cvt_pk_bf16_f32 v50, v2, v3
	v_cvt_pk_bf16_f32 v51, v4, v5
	v_cvt_pk_bf16_f32 v52, v6, v7
	v_cvt_pk_bf16_f32 v53, v8, v9
	v_cvt_pk_bf16_f32 v54, v10, v11
	v_cvt_pk_bf16_f32 v55, v12, v13
	v_cvt_pk_bf16_f32 v56, v14, v15
	v_cvt_pk_bf16_f32 v57, v16, v17
	s_waitcnt lgkmcnt(0)
	v_mfma_f32_32x32x16_bf16 v[18:33], v[58:61], v[50:53], 0
	v_mfma_f32_32x32x16_bf16 v[34:49], v[66:69], v[50:53], 0
	v_lshlrev_b32_e32 v178, 16, v200
	v_and_b32_e32 v179, 0xffff0000, v200
	v_lshlrev_b32_e32 v180, 16, v201
	v_and_b32_e32 v181, 0xffff0000, v201
	v_add_f32_e32 v174, 0, v178
	v_add_f32_e32 v175, 0, v179
	v_add_f32_e32 v176, 0, v180
	v_add_f32_e32 v177, 0, v181
	v_lshlrev_b32_e32 v178, 16, v202
	v_and_b32_e32 v179, 0xffff0000, v202
	v_lshlrev_b32_e32 v180, 16, v203
	v_and_b32_e32 v181, 0xffff0000, v203
	v_add_f32_e32 v174, v174, v178
	v_add_f32_e32 v175, v175, v179
	v_add_f32_e32 v176, v176, v180
	v_add_f32_e32 v177, v177, v181
	v_mfma_f32_32x32x16_bf16 v[18:33], v[62:65], v[54:57], v[18:33]
	v_mfma_f32_32x32x16_bf16 v[34:49], v[70:73], v[54:57], v[34:49]
	v_lshlrev_b32_e32 v178, 16, v204
	v_and_b32_e32 v179, 0xffff0000, v204
	v_lshlrev_b32_e32 v180, 16, v205
	v_and_b32_e32 v181, 0xffff0000, v205
	v_add_f32_e32 v174, v174, v178
	v_add_f32_e32 v175, v175, v179
	v_add_f32_e32 v176, v176, v180
	v_add_f32_e32 v177, v177, v181
	v_lshlrev_b32_e32 v178, 16, v206
	v_and_b32_e32 v179, 0xffff0000, v206
	v_lshlrev_b32_e32 v180, 16, v207
	v_and_b32_e32 v181, 0xffff0000, v207
	v_add_f32_e32 v174, v174, v178
	v_add_f32_e32 v175, v175, v179
	v_add_f32_e32 v176, v176, v180
	v_add_f32_e32 v177, v177, v181
	v_mul_f32_e32 v2, v190, v2
	v_mul_f32_e32 v3, v190, v3
	v_mul_f32_e32 v4, v190, v4
	v_mul_f32_e32 v5, v190, v5
	v_mul_f32_e32 v6, v190, v6
	v_mul_f32_e32 v7, v190, v7
	v_mul_f32_e32 v8, v190, v8
	v_mul_f32_e32 v9, v190, v9
	v_mul_f32_e32 v10, v190, v10
	v_mul_f32_e32 v11, v190, v11
	v_mul_f32_e32 v12, v190, v12
	v_mul_f32_e32 v13, v190, v13
	v_mul_f32_e32 v14, v190, v14
	v_mul_f32_e32 v15, v190, v15
	v_mul_f32_e32 v16, v190, v16
	v_mul_f32_e32 v17, v190, v17
	s_cmp_eq_u32 s7, 0
	s_cbranch_scc0 .Lp2b_in_30
	v_mfma_f32_32x32x16_bf16 v[18:33], v[74:77], v[166:169], v[18:33]
	s_branch .Lp2b_in_31

; __device__ __forceinline__ void scan_phase(const bf16* q, const bf16* kdT, const bf16* vT, const bf16* Pp, bf16* o, LAS unsigned char* lds, int bid, int G, int wave, int lane, int tid) {
;     ...
;         __syncthreads();
.Lp2b_in_31:
	v_lshlrev_b32_e32 v178, 16, v208
	v_and_b32_e32 v179, 0xffff0000, v208
	v_lshlrev_b32_e32 v180, 16, v209
	v_and_b32_e32 v181, 0xffff0000, v209
	v_add_f32_e32 v174, v174, v178
	v_add_f32_e32 v175, v175, v179
	v_add_f32_e32 v176, v176, v180
	v_add_f32_e32 v177, v177, v181
	v_lshlrev_b32_e32 v178, 16, v210
	v_and_b32_e32 v179, 0xffff0000, v210
	v_lshlrev_b32_e32 v180, 16, v211
	v_and_b32_e32 v181, 0xffff0000, v211
	v_add_f32_e32 v174, v174, v178
	v_add_f32_e32 v175, v175, v179
	v_add_f32_e32 v176, v176, v180
	v_add_f32_e32 v177, v177, v181
	v_mfma_f32_32x32x16_bf16 v[2:17], v[134:137], v[150:153], v[2:17]
	v_lshlrev_b32_e32 v178, 16, v212
	v_and_b32_e32 v179, 0xffff0000, v212
	v_lshlrev_b32_e32 v180, 16, v213
	v_and_b32_e32 v181, 0xffff0000, v213
	v_add_f32_e32 v174, v174, v178
	v_add_f32_e32 v175, v175, v179
	v_add_f32_e32 v176, v176, v180
	v_add_f32_e32 v177, v177, v181
	v_lshlrev_b32_e32 v178, 16, v214
	v_and_b32_e32 v179, 0xffff0000, v214
	v_lshlrev_b32_e32 v180, 16, v215
	v_and_b32_e32 v181, 0xffff0000, v215
	v_add_f32_e32 v174, v174, v178
	v_add_f32_e32 v175, v175, v179
	v_add_f32_e32 v176, v176, v180
	v_add_f32_e32 v177, v177, v181
	v_mfma_f32_32x32x16_bf16 v[2:17], v[138:141], v[154:157], v[2:17]
	v_mul_f32_e32 v174, v186, v174
	v_mul_f32_e32 v175, v187, v175
	v_mul_f32_e32 v176, v188, v176
	v_mul_f32_e32 v177, v189, v177
	v_bfe_u32 v178, v174, 16, 1
	v_bfe_u32 v179, v175, 16, 1
	v_bfe_u32 v180, v176, 16, 1
	v_bfe_u32 v181, v177, 16, 1
	v_add3_u32 v174, v174, v178, s23
	v_add3_u32 v175, v175, v179, s23
	v_add3_u32 v176, v176, v180, s23
	v_add3_u32 v177, v177, v181, s23
	global_store_short_d16_hi v197, v174, s[20:21] offset:-4096
	global_store_short_d16_hi v197, v175, s[20:21]
	global_store_short_d16_hi v198, v176, s[20:21] offset:-4096
	global_store_short_d16_hi v198, v177, s[20:21]
	s_add_u32 s20, s20, 0x40000
	s_addc_u32 s21, s21, 0
	v_cvt_pk_bf16_f32 v18, v18, v19
	v_cvt_pk_bf16_f32 v19, v20, v21
	v_cvt_pk_bf16_f32 v20, v22, v23
	v_cvt_pk_bf16_f32 v21, v24, v25
	v_cvt_pk_bf16_f32 v22, v26, v27
	v_cvt_pk_bf16_f32 v23, v28, v29
	v_cvt_pk_bf16_f32 v24, v30, v31
	v_cvt_pk_bf16_f32 v25, v32, v33
	ds_write_b128 v192, v[18:21] offset:32768
	ds_write_b128 v192, v[22:25] offset:33792
	v_mfma_f32_32x32x16_bf16 v[2:17], v[142:145], v[158:161], v[2:17]
	v_cvt_pk_bf16_f32 v34, v34, v35
	v_cvt_pk_bf16_f32 v35, v36, v37
	v_cvt_pk_bf16_f32 v36, v38, v39
	v_cvt_pk_bf16_f32 v37, v40, v41
	v_cvt_pk_bf16_f32 v38, v42, v43
	v_cvt_pk_bf16_f32 v39, v44, v45
	v_cvt_pk_bf16_f32 v40, v46, v47
	v_cvt_pk_bf16_f32 v41, v48, v49
	ds_write_b128 v192, v[34:37] offset:34816
	ds_write_b128 v192, v[38:41] offset:35840
	v_mfma_f32_32x32x16_bf16 v[2:17], v[146:149], v[162:165], v[2:17]
	s_waitcnt lgkmcnt(0)
	s_barrier
	ds_read2st64_b64 v[200:203], v193 offset0:64 offset1:72
	ds_read2st64_b64 v[204:207], v193 offset0:80 offset1:88
	ds_read2st64_b64 v[208:211], v193 offset0:96 offset1:104
	ds_read2st64_b64 v[212:215], v193 offset0:112 offset1:120
	s_waitcnt lgkmcnt(0)
	v_lshlrev_b32_e32 v178, 16, v200
	v_and_b32_e32 v179, 0xffff0000, v200
	v_lshlrev_b32_e32 v180, 16, v201
	v_and_b32_e32 v181, 0xffff0000, v201
	v_add_f32_e32 v174, 0, v178
	v_add_f32_e32 v175, 0, v179
	v_add_f32_e32 v176, 0, v180
	v_add_f32_e32 v177, 0, v181
	v_lshlrev_b32_e32 v178, 16, v202
	v_and_b32_e32 v179, 0xffff0000, v202
	v_lshlrev_b32_e32 v180, 16, v203
	v_and_b32_e32 v181, 0xffff0000, v203
	v_add_f32_e32 v174, v174, v178
	v_add_f32_e32 v175, v175, v179
	v_add_f32_e32 v176, v176, v180
	v_add_f32_e32 v177, v177, v181
	v_lshlrev_b32_e32 v178, 16, v204
	v_and_b32_e32 v179, 0xffff0000, v204
	v_lshlrev_b32_e32 v180, 16, v205
	v_and_b32_e32 v181, 0xffff0000, v205
	v_add_f32_e32 v174, v174, v178
	v_add_f32_e32 v175, v175, v179
	v_add_f32_e32 v176, v176, v180
	v_add_f32_e32 v177, v177, v181
	v_lshlrev_b32_e32 v178, 16, v206
	v_and_b32_e32 v179, 0xffff0000, v206
	v_lshlrev_b32_e32 v180, 16, v207
	v_and_b32_e32 v181, 0xffff0000, v207
	v_add_f32_e32 v174, v174, v178
	v_add_f32_e32 v175, v175, v179
	v_add_f32_e32 v176, v176, v180
	v_add_f32_e32 v177, v177, v181
	v_lshlrev_b32_e32 v178, 16, v208
	v_and_b32_e32 v179, 0xffff0000, v208
	v_lshlrev_b32_e32 v180, 16, v209
	v_and_b32_e32 v181, 0xffff0000, v209
	v_add_f32_e32 v174, v174, v178
	v_add_f32_e32 v175, v175, v179
	v_add_f32_e32 v176, v176, v180
	v_add_f32_e32 v177, v177, v181
	v_lshlrev_b32_e32 v178, 16, v210
	v_and_b32_e32 v179, 0xffff0000, v210
	v_lshlrev_b32_e32 v180, 16, v211
	v_and_b32_e32 v181, 0xffff0000, v211
	v_add_f32_e32 v174, v174, v178
	v_add_f32_e32 v175, v175, v179
	v_add_f32_e32 v176, v176, v180
	v_add_f32_e32 v177, v177, v181
	v_lshlrev_b32_e32 v178, 16, v212
	v_and_b32_e32 v179, 0xffff0000, v212
	v_lshlrev_b32_e32 v180, 16, v213
	v_and_b32_e32 v181, 0xffff0000, v213
	v_add_f32_e32 v174, v174, v178
	v_add_f32_e32 v175, v175, v179
	v_add_f32_e32 v176, v176, v180
	v_add_f32_e32 v177, v177, v181
	v_lshlrev_b32_e32 v178, 16, v214
	v_and_b32_e32 v179, 0xffff0000, v214
	v_lshlrev_b32_e32 v180, 16, v215
	v_and_b32_e32 v181, 0xffff0000, v215
	v_add_f32_e32 v174, v174, v178
	v_add_f32_e32 v175, v175, v179
	v_add_f32_e32 v176, v176, v180
	v_add_f32_e32 v177, v177, v181
	v_mul_f32_e32 v174, v186, v174
	v_mul_f32_e32 v175, v187, v175
	v_mul_f32_e32 v176, v188, v176
	v_mul_f32_e32 v177, v189, v177
	v_bfe_u32 v178, v174, 16, 1
	v_bfe_u32 v179, v175, 16, 1
	v_bfe_u32 v180, v176, 16, 1
	v_bfe_u32 v181, v177, 16, 1
	v_add3_u32 v174, v174, v178, s23
	v_add3_u32 v175, v175, v179, s23
	v_add3_u32 v176, v176, v180, s23
	v_add3_u32 v177, v177, v181, s23
	global_store_short_d16_hi v197, v174, s[20:21] offset:-4096
	global_store_short_d16_hi v197, v175, s[20:21]
	global_store_short_d16_hi v198, v176, s[20:21] offset:-4096
	global_store_short_d16_hi v198, v177, s[20:21]
	s_add_u32 s20, s20, 0x40000
	s_addc_u32 s21, s21, 0
	s_barrier
	s_branch .LBB0_718
